# mc_item<2> carried-state apply: fully unrolled, state loads prefetched 3 k-steps ahead with counted vmcnt, Q frags double-buffered
# speedup vs baseline: 1.0016x; 1.0006x over previous
; #define LAS __attribute__((address_space(3)))
; __device__ __forceinline__ unsigned pk2(float lo, float hi) { return pg8::cvt_pk_bf16(lo, hi); }
; __device__ __forceinline__ f32x4 mma16(bf16x8 a, bf16x8 b, f32x4 c) { return __builtin_amdgcn_mfma_f32_16x16x32_bf16(a, b, c, 0, 0, 0); }
; #define BSYNC() do { asm volatile("s_waitcnt vmcnt(0) lgkmcnt(0)" ::: "memory"); __syncthreads(); } while (0)
; template <int TY> __device__ __forceinline__ void mc_item(const Params& p, ldsp lds, int item) {
;     ...
;     for (int j = 0; j <= jc; ++j) { const size_t rowj = (size_t)b * 2048 + (sc * NB + j) * 64;
;         if constexpr (TY == 2) { st_rows<256>(KTs, PQ, kr, tid); st_T<512>(VTs, 72, vr, wave, lane); }
;         else { stage_rows<DK>(KTs, PQ, (const bf16_t*)(p.ws + WS_KT) + rowj * 768 + ecol, 768, tid);
;                stage_T<DV>(VTs, 72, Pb + rowj * PP + voff, PP, wave, lane); }
;         if constexpr (TY == 2) { __syncthreads(); if (j < jc) { const size_t rown = rowj + 64; ld_rows<256>(kr, Pb + rown * NO + O_K + h * 256, NO, tid); ld_T<512>(vr, Pb + rown * NO + voff, NO, wave, lane); } }
;         else BSYNC();
;         { f32x4 c0 = (f32x4){0.f, 0.f, 0.f, 0.f}, c1 = c0;
; #pragma unroll
;           for (int ks = 0; ks < DK / 32; ++ks) { const bf16x8 bq = ldfrag(QX, (16 * tt + l15) * PQ + 32 * ks + 8 * q4);
;               c0 = mma16(ldfrag(KTs, (16 * (2 * sp) + l15) * PQ + 32 * ks + 8 * q4), bq, c0);
;               c1 = mma16(ldfrag(KTs, (16 * (2 * sp + 1) + l15) * PQ + 32 * ks + 8 * q4), bq, c1); }
;           const int t = 16 * tt + l15;
;           const int tl = (j == jc) ? t : 4096;
; #pragma unroll
;           for (int jj = 0; jj < 4; ++jj) { if (32 * sp + 4 * q4 + jj > tl) c0[jj] = 0.f; if (32 * sp + 16 + 4 * q4 + jj > tl) c1[jj] = 0.f; }
;           u32x2 w; w.x = pk2(c0[0], c0[1]); w.y = pk2(c0[2], c0[3]); *(LAS u32x2*)(Pm + (size_t)(t * 72 + 32 * sp + 4 * q4) * 2) = w;
;           w.x = pk2(c1[0], c1[1]); w.y = pk2(c1[2], c1[3]); *(LAS u32x2*)(Pm + (size_t)(t * 72 + 32 * sp + 16 + 4 * q4) * 2) = w; }
;         if constexpr (TY == 2) __syncthreads(); else BSYNC();
.LBB0_862:
	v_add_u32_e32 v16, v211, v208
	s_waitcnt vmcnt(11)
	ds_write_b128 v16, v[130:133] offset:33792
	v_add_u32_e32 v16, v212, v209
	s_waitcnt vmcnt(10)
	ds_write_b128 v16, v[126:129] offset:33792
	v_add_u32_e32 v16, v213, v210
	s_waitcnt vmcnt(9)
	ds_write_b128 v16, v[122:125] offset:33792
	v_add_u32_e32 v16, v215, v214
	s_waitcnt vmcnt(8)
	ds_write_b128 v16, v[118:121] offset:33792
	s_waitcnt vmcnt(7)
	ds_write_b16 v206, v30
	ds_write_b16_d16_hi v206, v30 offset:144
	ds_write_b16 v206, v31 offset:288
	ds_write_b16_d16_hi v206, v31 offset:432
	ds_write_b16 v206, v32 offset:576
	ds_write_b16_d16_hi v206, v32 offset:720
	ds_write_b16 v206, v33 offset:864
	ds_write_b16_d16_hi v206, v33 offset:1008
	s_waitcnt vmcnt(6)
	ds_write_b16 v206, v22 offset:9216
	ds_write_b16_d16_hi v206, v22 offset:9360
	ds_write_b16 v206, v23 offset:9504
	ds_write_b16_d16_hi v206, v23 offset:9648
	ds_write_b16 v206, v24 offset:9792
	ds_write_b16_d16_hi v206, v24 offset:9936
	ds_write_b16 v206, v25 offset:10080
	ds_write_b16_d16_hi v206, v25 offset:10224
	s_waitcnt vmcnt(5)
	ds_write_b16 v206, v18 offset:18432
	ds_write_b16_d16_hi v206, v18 offset:18576
	ds_write_b16 v206, v19 offset:18720
	ds_write_b16_d16_hi v206, v19 offset:18864
	ds_write_b16 v206, v20 offset:19008
	ds_write_b16_d16_hi v206, v20 offset:19152
	ds_write_b16 v206, v21 offset:19296
	ds_write_b16_d16_hi v206, v21 offset:19440
	s_waitcnt vmcnt(4)
	ds_write_b16 v206, v12 offset:27648
	ds_write_b16_d16_hi v206, v12 offset:27792
	ds_write_b16 v206, v13 offset:27936
	ds_write_b16_d16_hi v206, v13 offset:28080
	ds_write_b16 v206, v14 offset:28224
	ds_write_b16_d16_hi v206, v14 offset:28368
	ds_write_b16 v206, v15 offset:28512
	ds_write_b16_d16_hi v206, v15 offset:28656
	s_waitcnt vmcnt(3)
	ds_write_b16 v206, v8 offset:36864
	ds_write_b16_d16_hi v206, v8 offset:37008
	ds_write_b16 v206, v9 offset:37152
	ds_write_b16_d16_hi v206, v9 offset:37296
	ds_write_b16 v206, v10 offset:37440
	ds_write_b16_d16_hi v206, v10 offset:37584
	ds_write_b16 v206, v11 offset:37728
	ds_write_b16_d16_hi v206, v11 offset:37872
	s_waitcnt vmcnt(2)
	ds_write_b16 v206, v4 offset:46080
	ds_write_b16_d16_hi v206, v4 offset:46224
	ds_write_b16 v206, v5 offset:46368
	ds_write_b16_d16_hi v206, v5 offset:46512
	ds_write_b16 v206, v6 offset:46656
	ds_write_b16_d16_hi v206, v6 offset:46800
	ds_write_b16 v206, v7 offset:46944
	ds_write_b16_d16_hi v206, v7 offset:47088
	s_waitcnt vmcnt(1)
	ds_write_b16 v206, v0 offset:55296
	ds_write_b16_d16_hi v206, v0 offset:55440
	ds_write_b16 v206, v1 offset:55584
	ds_write_b16_d16_hi v206, v1 offset:55728
	ds_write_b16 v206, v2 offset:55872
	ds_write_b16_d16_hi v206, v2 offset:56016
	ds_write_b16 v206, v3 offset:56160
	ds_write_b16_d16_hi v206, v3 offset:56304
	s_waitcnt vmcnt(0)
	ds_write_b16 v206, v114 offset:64512
	ds_write_b16_d16_hi v206, v114 offset:64656
	ds_write_b16 v206, v115 offset:64800
	ds_write_b16_d16_hi v206, v115 offset:64944
	ds_write_b16 v206, v116 offset:65088
	ds_write_b16_d16_hi v206, v116 offset:65232
	ds_write_b16 v206, v117 offset:65376
	ds_write_b16_d16_hi v206, v117 offset:65520
	v_add_u32_e32 v16, 0, v207
	v_add_u32_e32 v18, 0, v217
	v_add_u32_e32 v19, 0, v216
	s_waitcnt lgkmcnt(0)
	s_barrier
	ds_read_b128 v[0:3], v16
	ds_read_b128 v[4:7], v18 offset:33792
	ds_read_b128 v[8:11], v19 offset:33792
	s_waitcnt lgkmcnt(1)
	v_mfma_f32_16x16x32_bf16 v[4:7], v[4:7], v[0:3], 0
	v_cmp_gt_i32_e32 vcc, v157, v155
	v_or_b32_e32 v146, 16, v150
	v_mad_u32_u24 v74, v146, s9, v154
	s_waitcnt lgkmcnt(0)
	v_mfma_f32_16x16x32_bf16 v[0:3], v[8:11], v[0:3], 0
	ds_read_b128 v[8:11], v16 offset:64
	ds_read_b128 v[12:15], v18 offset:33856
	v_add_u32_e32 v75, v139, v162
	v_add_u32_e32 v90, v139, v160
	s_waitcnt lgkmcnt(0)
	v_mfma_f32_16x16x32_bf16 v[4:7], v[12:15], v[8:11], v[4:7]
	ds_read_b128 v[12:15], v19 offset:33856
	v_add_u32_e32 v131, v139, v158
	v_add_u32_e32 v130, v139, v159
	s_waitcnt lgkmcnt(0)
	v_mfma_f32_16x16x32_bf16 v[0:3], v[12:15], v[8:11], v[0:3]
	ds_read_b128 v[8:11], v16 offset:128
	ds_read_b128 v[12:15], v18 offset:33920
	v_readlane_b32 s0, v253, 44
	v_readlane_b32 s1, v253, 45
	s_waitcnt lgkmcnt(0)
	v_mfma_f32_16x16x32_bf16 v[4:7], v[12:15], v[8:11], v[4:7]
	ds_read_b128 v[12:15], v19 offset:33920
	s_waitcnt lgkmcnt(0)
	v_mfma_f32_16x16x32_bf16 v[0:3], v[12:15], v[8:11], v[0:3]
	ds_read_b128 v[8:11], v16 offset:192
	ds_read_b128 v[12:15], v18 offset:33984
	s_waitcnt lgkmcnt(0)
	v_mfma_f32_16x16x32_bf16 v[4:7], v[12:15], v[8:11], v[4:7]
	ds_read_b128 v[12:15], v19 offset:33984
	s_waitcnt lgkmcnt(0)
	v_mfma_f32_16x16x32_bf16 v[0:3], v[12:15], v[8:11], v[0:3]
	ds_read_b128 v[8:11], v16 offset:256
	ds_read_b128 v[12:15], v18 offset:34048
	s_waitcnt lgkmcnt(0)
	v_mfma_f32_16x16x32_bf16 v[4:7], v[12:15], v[8:11], v[4:7]
	ds_read_b128 v[12:15], v19 offset:34048
	s_waitcnt lgkmcnt(0)
	v_mfma_f32_16x16x32_bf16 v[0:3], v[12:15], v[8:11], v[0:3]
	ds_read_b128 v[8:11], v16 offset:320
	ds_read_b128 v[12:15], v18 offset:34112
	s_waitcnt lgkmcnt(0)
	v_mfma_f32_16x16x32_bf16 v[4:7], v[12:15], v[8:11], v[4:7]
	ds_read_b128 v[12:15], v19 offset:34112
	s_waitcnt lgkmcnt(0)
	v_mfma_f32_16x16x32_bf16 v[0:3], v[12:15], v[8:11], v[0:3]
	ds_read_b128 v[8:11], v16 offset:384
	ds_read_b128 v[12:15], v18 offset:34176
	s_waitcnt lgkmcnt(0)
	v_mfma_f32_16x16x32_bf16 v[4:7], v[12:15], v[8:11], v[4:7]
	ds_read_b128 v[12:15], v19 offset:34176
	s_waitcnt lgkmcnt(0)
	v_mfma_f32_16x16x32_bf16 v[0:3], v[12:15], v[8:11], v[0:3]
	ds_read_b128 v[8:11], v16 offset:448
	ds_read_b128 v[12:15], v18 offset:34240
	v_add_u32_e32 v16, v154, v163
	s_waitcnt lgkmcnt(0)
	v_mfma_f32_16x16x32_bf16 v[4:7], v[12:15], v[8:11], v[4:7]
	ds_read_b128 v[12:15], v19 offset:34240
	s_waitcnt lgkmcnt(0)
	v_mfma_f32_16x16x32_bf16 v[0:3], v[12:15], v[8:11], v[0:3]
	v_mov_b32_e32 v8, s41
	s_nop 3
	v_cndmask_b32_e32 v9, v4, v8, vcc
	v_cmp_gt_i32_e32 vcc, v205, v155
	s_nop 1
	v_cndmask_b32_e32 v8, v0, v8, vcc
	v_cmp_lt_i32_e32 vcc, v157, v155
	s_nop 1
	v_cndmask_b32_e32 v0, v9, v4, vcc
	v_cndmask_b32_e32 v4, 0, v5, vcc
	v_cmp_le_i32_e32 vcc, v204, v155
	v_cvt_pk_bf16_f32 v0, v0, v4
	v_add_u32_e32 v4, 0, v156
	v_add_u32_e32 v4, 0x22800, v4
	v_cndmask_b32_e32 v5, 0, v1, vcc
	v_or_b32_e32 v1, 2, v157
	v_cmp_le_i32_e32 vcc, v1, v155
	s_nop 1
	v_cndmask_b32_e32 v1, 0, v6, vcc
	v_cmp_le_i32_e32 vcc, v201, v155
	s_nop 1
	v_cndmask_b32_e32 v2, 0, v2, vcc
	v_cmp_le_i32_e32 vcc, v202, v155
	s_nop 1
	v_cndmask_b32_e32 v6, 0, v7, vcc
	v_cmp_le_i32_e32 vcc, v203, v155
	v_cvt_pk_bf16_f32 v1, v1, v6
	ds_write_b64 v4, v[0:1]
	v_cvt_pk_bf16_f32 v0, v8, v5
	s_nop 0
	v_cndmask_b32_e32 v3, 0, v3, vcc
	v_cvt_pk_bf16_f32 v1, v2, v3
	ds_write_b64 v4, v[0:1] offset:32
	s_waitcnt lgkmcnt(0)
	s_barrier
; __device__ __forceinline__ f32x4 mma16(bf16x8 a, bf16x8 b, f32x4 c) { return __builtin_amdgcn_mfma_f32_16x16x32_bf16(a, b, c, 0, 0, 0); }
; #define BSYNC() do { asm volatile("s_waitcnt vmcnt(0) lgkmcnt(0)" ::: "memory"); __syncthreads(); } while (0)
; template <int TY> __device__ __forceinline__ void mc_item(const Params& p, ldsp lds, int item) {
;     ...
;         if constexpr (TY == 2) __syncthreads(); else BSYNC();
; #pragma unroll
;         for (int ks = 0; ks < 2; ++ks) { bf16x8 pb[4];
; #pragma unroll
;             for (int tk = 0; tk < 4; ++tk) pb[tk] = ldfrag(Pm, (16 * tk + l15) * 72 + 32 * ks + 8 * q4);
; #pragma unroll
;             for (int ei = 0; ei < ET; ++ei) { const bf16x8 va = ldfrag(VTs, (16 * (wave * ET + ei) + l15) * 72 + 32 * ks + 8 * q4);
; #pragma unroll
;                 for (int tk = 0; tk < 4; ++tk) acc[ei][tk] = mma16(va, pb[tk], acc[ei][tk]); } }
;         if constexpr (TY == 2) __syncthreads(); else BSYNC(); }
;     if ((TY == 2 ? sc : c) != 0) { const bf16_t* STp = (TY == 2) ? (const bf16_t*)(p.ws + WS_ST) + ((size_t)bh * 8 + sc) * 512 * 256
;                                     : (const bf16_t*)(p.ws + WS_ST + (TY ? ST_HGRN : 0)) + ((size_t)bh * 32 + c) * 128 * DK;
;       ldsp QS = (TY == 2) ? QX : QH2;
;       bf16x8 sa[ET], sn[ET];
; #pragma unroll
;       for (int ei = 0; ei < ET; ++ei) sa[ei] = *(const bf16x8*)(STp + (size_t)(16 * (wave * ET + ei) + l15) * DK + 8 * q4);
; #pragma unroll 1
;       for (int ks = 0; ks < DK / 32; ++ks) { bf16x8 qb[4];
;           const int kn = (ks + 1 < DK / 32) ? ks + 1 : ks;
; #pragma unroll
;           for (int ei = 0; ei < ET; ++ei) sn[ei] = *(const bf16x8*)(STp + (size_t)(16 * (wave * ET + ei) + l15) * DK + 32 * kn + 8 * q4);
; #pragma unroll
;           for (int tk = 0; tk < 4; ++tk) qb[tk] = ldfrag(QS, (16 * tk + l15) * PQ + 32 * ks + 8 * q4);
	ds_read_b128 v[0:3], v16
	ds_read_b128 v[4:7], v74
	ds_read_b128 v[8:11], v74 offset:2304
	ds_read_b128 v[12:15], v74 offset:4608
	ds_read_b128 v[18:21], v75
	ds_read_b128 v[62:65], v131
	s_waitcnt lgkmcnt(1)
	v_mfma_f32_16x16x32_bf16 v[22:25], v[18:21], v[0:3], v[42:45]
	s_and_b64 vcc, exec, s[0:1]
	v_mfma_f32_16x16x32_bf16 v[30:33], v[18:21], v[4:7], v[38:41]
	v_mfma_f32_16x16x32_bf16 v[34:37], v[18:21], v[8:11], v[34:37]
	v_mfma_f32_16x16x32_bf16 v[18:21], v[18:21], v[12:15], v[26:29]
	s_nop 2
	ds_read_b128 v[26:29], v90
	s_waitcnt lgkmcnt(0)
	v_mfma_f32_16x16x32_bf16 v[42:45], v[26:29], v[4:7], v[50:53]
	s_nop 2
	ds_read_b128 v[50:53], v130
	ds_read_b128 v[114:117], v16 offset:64
	ds_read_b128 v[118:121], v74 offset:64
	ds_read_b128 v[122:125], v74 offset:2368
	ds_read_b128 v[126:129], v74 offset:4672
	ds_read_b128 v[78:81], v75 offset:64
	v_mfma_f32_16x16x32_bf16 v[38:41], v[26:29], v[0:3], v[46:49]
	v_mfma_f32_16x16x32_bf16 v[46:49], v[26:29], v[8:11], v[54:57]
	v_mfma_f32_16x16x32_bf16 v[26:29], v[26:29], v[12:15], v[58:61]
	s_waitcnt lgkmcnt(5)
	v_mfma_f32_16x16x32_bf16 v[54:57], v[50:53], v[0:3], v[66:69]
	v_mfma_f32_16x16x32_bf16 v[58:61], v[50:53], v[4:7], v[70:73]
	v_mfma_f32_16x16x32_bf16 v[66:69], v[50:53], v[8:11], v[82:85]
	v_mfma_f32_16x16x32_bf16 v[50:53], v[50:53], v[12:15], v[86:89]
	v_mfma_f32_16x16x32_bf16 v[0:3], v[62:65], v[0:3], v[98:101]
	v_mfma_f32_16x16x32_bf16 v[4:7], v[62:65], v[4:7], v[102:105]
	v_mfma_f32_16x16x32_bf16 v[8:11], v[62:65], v[8:11], v[106:109]
	v_mfma_f32_16x16x32_bf16 v[12:15], v[62:65], v[12:15], v[110:113]
	s_waitcnt lgkmcnt(0)
	v_mfma_f32_16x16x32_bf16 v[62:65], v[78:81], v[114:117], v[22:25]
	v_mfma_f32_16x16x32_bf16 v[70:73], v[78:81], v[118:121], v[30:33]
	v_mfma_f32_16x16x32_bf16 v[74:77], v[78:81], v[122:125], v[34:37]
	v_mfma_f32_16x16x32_bf16 v[78:81], v[78:81], v[126:129], v[18:21]
	s_nop 2
	ds_read_b128 v[18:21], v90 offset:64
	s_waitcnt lgkmcnt(0)
	v_mfma_f32_16x16x32_bf16 v[82:85], v[18:21], v[114:117], v[38:41]
	v_mfma_f32_16x16x32_bf16 v[86:89], v[18:21], v[118:121], v[42:45]
	v_mfma_f32_16x16x32_bf16 v[90:93], v[18:21], v[122:125], v[46:49]
	v_mfma_f32_16x16x32_bf16 v[94:97], v[18:21], v[126:129], v[26:29]
	ds_read_b128 v[18:21], v130 offset:64
	s_waitcnt lgkmcnt(0)
	v_mfma_f32_16x16x32_bf16 v[98:101], v[18:21], v[114:117], v[54:57]
	v_mfma_f32_16x16x32_bf16 v[102:105], v[18:21], v[118:121], v[58:61]
	v_mfma_f32_16x16x32_bf16 v[106:109], v[18:21], v[122:125], v[66:69]
	v_mfma_f32_16x16x32_bf16 v[110:113], v[18:21], v[126:129], v[50:53]
	ds_read_b128 v[18:21], v131 offset:64
	s_waitcnt lgkmcnt(0)
	s_barrier
	v_mfma_f32_16x16x32_bf16 v[114:117], v[18:21], v[114:117], v[0:3]
	v_mfma_f32_16x16x32_bf16 v[118:121], v[18:21], v[118:121], v[4:7]
	v_mfma_f32_16x16x32_bf16 v[122:125], v[18:21], v[122:125], v[8:11]
	v_mfma_f32_16x16x32_bf16 v[126:129], v[18:21], v[126:129], v[12:15]
	s_cbranch_vccz .LBB0_876
	s_ashr_i32 s9, s8, 31
	s_lshl_b64 s[0:1], s[8:9], 21
	v_readlane_b32 s8, v253, 47
	s_add_u32 s0, s8, s0
	v_readlane_b32 s8, v253, 48
	s_addc_u32 s1, s8, s1
	s_and_b32 s8, s60, 0xffffffc0
	v_or_b32_e32 v0, s8, v150
	v_or_b32_e32 v2, 16, v0
	v_ashrrev_i32_e32 v1, 31, v0
	v_ashrrev_i32_e32 v3, 31, v2
	v_lshlrev_b32_e32 v16, 1, v138
	v_lshlrev_b64 v[132:133], 9, v[0:1]
	v_lshlrev_b64 v[138:139], 9, v[2:3]
	v_or_b32_e32 v2, 32, v0
	v_or_b32_e32 v0, 48, v0
	v_ashrrev_i32_e32 v1, 31, v0
	v_ashrrev_i32_e32 v3, 31, v2
	v_lshlrev_b64 v[142:143], 9, v[0:1]
	v_mul_u32_u24_e32 v0, 0x210, v150
	v_lshl_add_u64 v[130:131], s[0:1], 0, v[16:17]
	v_lshlrev_b64 v[140:141], 9, v[2:3]
	v_add3_u32 v16, v0, v153, 0
	v_lshl_add_u64 v[202:203], v[130:131], 0, v[132:133]
	v_lshl_add_u64 v[210:211], v[130:131], 0, v[138:139]
	v_lshl_add_u64 v[250:251], v[130:131], 0, v[140:141]
	v_lshl_add_u64 v[148:149], v[130:131], 0, v[142:143]
	global_load_dwordx4 v[186:189], v[202:203], off
	global_load_dwordx4 v[190:193], v[210:211], off
	global_load_dwordx4 v[194:197], v[250:251], off
	global_load_dwordx4 v[198:201], v[148:149], off
	global_load_dwordx4 v[206:209], v[202:203], off offset:64
	global_load_dwordx4 v[246:249], v[210:211], off offset:64
	global_load_dwordx4 v[134:137], v[250:251], off offset:64
	global_load_dwordx4 v[154:157], v[148:149], off offset:64
	global_load_dwordx4 v[172:175], v[202:203], off offset:128
	global_load_dwordx4 v[176:179], v[210:211], off offset:128
	global_load_dwordx4 v[180:183], v[250:251], off offset:128
	global_load_dwordx4 v[166:169], v[148:149], off offset:128
	ds_read_b128 v[214:217], v16
	ds_read_b128 v[218:221], v16 offset:8448
	ds_read_b128 v[222:225], v16 offset:16896
	ds_read_b128 v[226:229], v16 offset:25344
	v_mov_b64_e32 v[50:51], v[78:79]
	v_mov_b64_e32 v[54:55], v[74:75]
	v_mov_b64_e32 v[58:59], v[70:71]
	v_mov_b64_e32 v[68:69], v[64:65]
	v_mov_b64_e32 v[46:47], v[82:83]
	v_mov_b64_e32 v[42:43], v[86:87]
	v_mov_b64_e32 v[38:39], v[90:91]
	v_mov_b64_e32 v[34:35], v[94:95]
	v_mov_b64_e32 v[30:31], v[98:99]
	v_mov_b64_e32 v[26:27], v[102:103]
	v_mov_b64_e32 v[22:23], v[106:107]
	v_mov_b64_e32 v[18:19], v[110:111]
	v_mov_b64_e32 v[12:13], v[114:115]
	v_mov_b64_e32 v[8:9], v[118:119]
	v_mov_b64_e32 v[4:5], v[122:123]
	v_mov_b64_e32 v[0:1], v[126:127]
	s_mov_b32 s0, 32
	v_mov_b64_e32 v[52:53], v[80:81]
	v_mov_b64_e32 v[56:57], v[76:77]
	v_mov_b64_e32 v[60:61], v[72:73]
	v_mov_b64_e32 v[66:67], v[62:63]
	v_mov_b64_e32 v[144:145], v[130:131]
	v_mov_b64_e32 v[48:49], v[84:85]
	v_mov_b64_e32 v[44:45], v[88:89]
	v_mov_b64_e32 v[40:41], v[92:93]
	v_mov_b64_e32 v[36:37], v[96:97]
	v_mov_b64_e32 v[32:33], v[100:101]
	v_mov_b64_e32 v[28:29], v[104:105]
	v_mov_b64_e32 v[24:25], v[108:109]
	v_mov_b64_e32 v[20:21], v[112:113]
	v_mov_b64_e32 v[14:15], v[116:117]
	v_mov_b64_e32 v[10:11], v[120:121]
	v_mov_b64_e32 v[6:7], v[124:125]
	v_mov_b64_e32 v[2:3], v[128:129]
; __device__ __forceinline__ f32x4 mma16(bf16x8 a, bf16x8 b, f32x4 c) { return __builtin_amdgcn_mfma_f32_16x16x32_bf16(a, b, c, 0, 0, 0); }
; template <int TY> __device__ __forceinline__ void mc_item(const Params& p, ldsp lds, int item) {
;     ...
; #pragma unroll 1
;       for (int ks = 0; ks < DK / 32; ++ks) { bf16x8 qb[4];
;           const int kn = (ks + 1 < DK / 32) ? ks + 1 : ks;
; #pragma unroll
;           for (int ei = 0; ei < ET; ++ei) sn[ei] = *(const bf16x8*)(STp + (size_t)(16 * (wave * ET + ei) + l15) * DK + 32 * kn + 8 * q4);
; #pragma unroll
;           for (int tk = 0; tk < 4; ++tk) qb[tk] = ldfrag(QS, (16 * tk + l15) * PQ + 32 * ks + 8 * q4);
; #pragma unroll
;           for (int ei = 0; ei < ET; ++ei) {
; #pragma unroll
;               for (int tk = 0; tk < 4; ++tk) acc[ei][tk] = mma16(sa[ei], qb[tk], acc[ei][tk]); }
; #pragma unroll
;           for (int ei = 0; ei < ET; ++ei) sa[ei] = sn[ei]; } }
.LBB0_864:
	ds_read_b128 v[230:233], v16 offset:64
	ds_read_b128 v[234:237], v16 offset:8512
	ds_read_b128 v[238:241], v16 offset:16960
	ds_read_b128 v[242:245], v16 offset:25408
	s_waitcnt vmcnt(11) lgkmcnt(4)
	v_mfma_f32_16x16x32_bf16 v[66:69], v[186:189], v[214:217], v[66:69]
	v_mfma_f32_16x16x32_bf16 v[58:61], v[186:189], v[218:221], v[58:61]
	v_mfma_f32_16x16x32_bf16 v[54:57], v[186:189], v[222:225], v[54:57]
	v_mfma_f32_16x16x32_bf16 v[50:53], v[186:189], v[226:229], v[50:53]
	global_load_dwordx4 v[186:189], v[202:203], off offset:192
	s_waitcnt vmcnt(11)
	v_mfma_f32_16x16x32_bf16 v[46:49], v[190:193], v[214:217], v[46:49]
	v_mfma_f32_16x16x32_bf16 v[42:45], v[190:193], v[218:221], v[42:45]
	v_mfma_f32_16x16x32_bf16 v[38:41], v[190:193], v[222:225], v[38:41]
	v_mfma_f32_16x16x32_bf16 v[34:37], v[190:193], v[226:229], v[34:37]
	global_load_dwordx4 v[190:193], v[210:211], off offset:192
	s_waitcnt vmcnt(11)
	v_mfma_f32_16x16x32_bf16 v[30:33], v[194:197], v[214:217], v[30:33]
	v_mfma_f32_16x16x32_bf16 v[26:29], v[194:197], v[218:221], v[26:29]
	v_mfma_f32_16x16x32_bf16 v[22:25], v[194:197], v[222:225], v[22:25]
	v_mfma_f32_16x16x32_bf16 v[18:21], v[194:197], v[226:229], v[18:21]
	global_load_dwordx4 v[194:197], v[250:251], off offset:192
	s_waitcnt vmcnt(11)
	v_mfma_f32_16x16x32_bf16 v[12:15], v[198:201], v[214:217], v[12:15]
	v_mfma_f32_16x16x32_bf16 v[8:11], v[198:201], v[218:221], v[8:11]
	v_mfma_f32_16x16x32_bf16 v[4:7], v[198:201], v[222:225], v[4:7]
	v_mfma_f32_16x16x32_bf16 v[0:3], v[198:201], v[226:229], v[0:3]
	global_load_dwordx4 v[198:201], v[148:149], off offset:192
	ds_read_b128 v[214:217], v16 offset:128
	ds_read_b128 v[218:221], v16 offset:8576
	ds_read_b128 v[222:225], v16 offset:17024
	ds_read_b128 v[226:229], v16 offset:25472
	s_waitcnt vmcnt(11) lgkmcnt(4)
	v_mfma_f32_16x16x32_bf16 v[66:69], v[206:209], v[230:233], v[66:69]
	v_mfma_f32_16x16x32_bf16 v[58:61], v[206:209], v[234:237], v[58:61]
	v_mfma_f32_16x16x32_bf16 v[54:57], v[206:209], v[238:241], v[54:57]
	v_mfma_f32_16x16x32_bf16 v[50:53], v[206:209], v[242:245], v[50:53]
	global_load_dwordx4 v[206:209], v[202:203], off offset:256
	s_waitcnt vmcnt(11)
	v_mfma_f32_16x16x32_bf16 v[46:49], v[246:249], v[230:233], v[46:49]
	v_mfma_f32_16x16x32_bf16 v[42:45], v[246:249], v[234:237], v[42:45]
	v_mfma_f32_16x16x32_bf16 v[38:41], v[246:249], v[238:241], v[38:41]
	v_mfma_f32_16x16x32_bf16 v[34:37], v[246:249], v[242:245], v[34:37]
	global_load_dwordx4 v[246:249], v[210:211], off offset:256
	s_waitcnt vmcnt(11)
	v_mfma_f32_16x16x32_bf16 v[30:33], v[134:137], v[230:233], v[30:33]
	v_mfma_f32_16x16x32_bf16 v[26:29], v[134:137], v[234:237], v[26:29]
	v_mfma_f32_16x16x32_bf16 v[22:25], v[134:137], v[238:241], v[22:25]
	v_mfma_f32_16x16x32_bf16 v[18:21], v[134:137], v[242:245], v[18:21]
	global_load_dwordx4 v[134:137], v[250:251], off offset:256
	s_waitcnt vmcnt(11)
	v_mfma_f32_16x16x32_bf16 v[12:15], v[154:157], v[230:233], v[12:15]
	v_mfma_f32_16x16x32_bf16 v[8:11], v[154:157], v[234:237], v[8:11]
	v_mfma_f32_16x16x32_bf16 v[4:7], v[154:157], v[238:241], v[4:7]
	v_mfma_f32_16x16x32_bf16 v[0:3], v[154:157], v[242:245], v[0:3]
	global_load_dwordx4 v[154:157], v[148:149], off offset:256
	ds_read_b128 v[230:233], v16 offset:192
	ds_read_b128 v[234:237], v16 offset:8640
	ds_read_b128 v[238:241], v16 offset:17088
	ds_read_b128 v[242:245], v16 offset:25536
	s_waitcnt vmcnt(11) lgkmcnt(4)
	v_mfma_f32_16x16x32_bf16 v[66:69], v[172:175], v[214:217], v[66:69]
	v_mfma_f32_16x16x32_bf16 v[58:61], v[172:175], v[218:221], v[58:61]
	v_mfma_f32_16x16x32_bf16 v[54:57], v[172:175], v[222:225], v[54:57]
	v_mfma_f32_16x16x32_bf16 v[50:53], v[172:175], v[226:229], v[50:53]
	global_load_dwordx4 v[172:175], v[202:203], off offset:320
	s_waitcnt vmcnt(11)
	v_mfma_f32_16x16x32_bf16 v[46:49], v[176:179], v[214:217], v[46:49]
	v_mfma_f32_16x16x32_bf16 v[42:45], v[176:179], v[218:221], v[42:45]
	v_mfma_f32_16x16x32_bf16 v[38:41], v[176:179], v[222:225], v[38:41]
	v_mfma_f32_16x16x32_bf16 v[34:37], v[176:179], v[226:229], v[34:37]
	global_load_dwordx4 v[176:179], v[210:211], off offset:320
	s_waitcnt vmcnt(11)
	v_mfma_f32_16x16x32_bf16 v[30:33], v[180:183], v[214:217], v[30:33]
	v_mfma_f32_16x16x32_bf16 v[26:29], v[180:183], v[218:221], v[26:29]
	v_mfma_f32_16x16x32_bf16 v[22:25], v[180:183], v[222:225], v[22:25]
	v_mfma_f32_16x16x32_bf16 v[18:21], v[180:183], v[226:229], v[18:21]
	global_load_dwordx4 v[180:183], v[250:251], off offset:320
	s_waitcnt vmcnt(11)
	v_mfma_f32_16x16x32_bf16 v[12:15], v[166:169], v[214:217], v[12:15]
	v_mfma_f32_16x16x32_bf16 v[8:11], v[166:169], v[218:221], v[8:11]
	v_mfma_f32_16x16x32_bf16 v[4:7], v[166:169], v[222:225], v[4:7]
	v_mfma_f32_16x16x32_bf16 v[0:3], v[166:169], v[226:229], v[0:3]
	global_load_dwordx4 v[166:169], v[148:149], off offset:320
	ds_read_b128 v[214:217], v16 offset:256
	ds_read_b128 v[218:221], v16 offset:8704
	ds_read_b128 v[222:225], v16 offset:17152
	ds_read_b128 v[226:229], v16 offset:25600
	s_waitcnt vmcnt(11) lgkmcnt(4)
	v_mfma_f32_16x16x32_bf16 v[66:69], v[186:189], v[230:233], v[66:69]
	v_mfma_f32_16x16x32_bf16 v[58:61], v[186:189], v[234:237], v[58:61]
	v_mfma_f32_16x16x32_bf16 v[54:57], v[186:189], v[238:241], v[54:57]
	v_mfma_f32_16x16x32_bf16 v[50:53], v[186:189], v[242:245], v[50:53]
	global_load_dwordx4 v[186:189], v[202:203], off offset:384
	s_waitcnt vmcnt(11)
	v_mfma_f32_16x16x32_bf16 v[46:49], v[190:193], v[230:233], v[46:49]
	v_mfma_f32_16x16x32_bf16 v[42:45], v[190:193], v[234:237], v[42:45]
	v_mfma_f32_16x16x32_bf16 v[38:41], v[190:193], v[238:241], v[38:41]
	v_mfma_f32_16x16x32_bf16 v[34:37], v[190:193], v[242:245], v[34:37]
	global_load_dwordx4 v[190:193], v[210:211], off offset:384
	s_waitcnt vmcnt(11)
; __device__ __forceinline__ f32x4 mma16(bf16x8 a, bf16x8 b, f32x4 c) { return __builtin_amdgcn_mfma_f32_16x16x32_bf16(a, b, c, 0, 0, 0); }
; template <int TY> __device__ __forceinline__ void mc_item(const Params& p, ldsp lds, int item) {
;     ...
; #pragma unroll 1
;       for (int ks = 0; ks < DK / 32; ++ks) { bf16x8 qb[4];
;           const int kn = (ks + 1 < DK / 32) ? ks + 1 : ks;
; #pragma unroll
;           for (int ei = 0; ei < ET; ++ei) sn[ei] = *(const bf16x8*)(STp + (size_t)(16 * (wave * ET + ei) + l15) * DK + 32 * kn + 8 * q4);
; #pragma unroll
;           for (int tk = 0; tk < 4; ++tk) qb[tk] = ldfrag(QS, (16 * tk + l15) * PQ + 32 * ks + 8 * q4);
; #pragma unroll
;           for (int ei = 0; ei < ET; ++ei) {
; #pragma unroll
;               for (int tk = 0; tk < 4; ++tk) acc[ei][tk] = mma16(sa[ei], qb[tk], acc[ei][tk]); }
; #pragma unroll
;           for (int ei = 0; ei < ET; ++ei) sa[ei] = sn[ei]; } }
	v_mfma_f32_16x16x32_bf16 v[30:33], v[194:197], v[230:233], v[30:33]
	v_mfma_f32_16x16x32_bf16 v[26:29], v[194:197], v[234:237], v[26:29]
	v_mfma_f32_16x16x32_bf16 v[22:25], v[194:197], v[238:241], v[22:25]
	v_mfma_f32_16x16x32_bf16 v[18:21], v[194:197], v[242:245], v[18:21]
	global_load_dwordx4 v[194:197], v[250:251], off offset:384
	s_waitcnt vmcnt(11)
	v_mfma_f32_16x16x32_bf16 v[12:15], v[198:201], v[230:233], v[12:15]
	v_mfma_f32_16x16x32_bf16 v[8:11], v[198:201], v[234:237], v[8:11]
	v_mfma_f32_16x16x32_bf16 v[4:7], v[198:201], v[238:241], v[4:7]
	v_mfma_f32_16x16x32_bf16 v[0:3], v[198:201], v[242:245], v[0:3]
	global_load_dwordx4 v[198:201], v[148:149], off offset:384
	ds_read_b128 v[230:233], v16 offset:320
	ds_read_b128 v[234:237], v16 offset:8768
	ds_read_b128 v[238:241], v16 offset:17216
	ds_read_b128 v[242:245], v16 offset:25664
	s_waitcnt vmcnt(11) lgkmcnt(4)
	v_mfma_f32_16x16x32_bf16 v[66:69], v[206:209], v[214:217], v[66:69]
	v_mfma_f32_16x16x32_bf16 v[58:61], v[206:209], v[218:221], v[58:61]
	v_mfma_f32_16x16x32_bf16 v[54:57], v[206:209], v[222:225], v[54:57]
	v_mfma_f32_16x16x32_bf16 v[50:53], v[206:209], v[226:229], v[50:53]
	global_load_dwordx4 v[206:209], v[202:203], off offset:448
	s_waitcnt vmcnt(11)
	v_mfma_f32_16x16x32_bf16 v[46:49], v[246:249], v[214:217], v[46:49]
	v_mfma_f32_16x16x32_bf16 v[42:45], v[246:249], v[218:221], v[42:45]
	v_mfma_f32_16x16x32_bf16 v[38:41], v[246:249], v[222:225], v[38:41]
	v_mfma_f32_16x16x32_bf16 v[34:37], v[246:249], v[226:229], v[34:37]
	global_load_dwordx4 v[246:249], v[210:211], off offset:448
	s_waitcnt vmcnt(11)
	v_mfma_f32_16x16x32_bf16 v[30:33], v[134:137], v[214:217], v[30:33]
	v_mfma_f32_16x16x32_bf16 v[26:29], v[134:137], v[218:221], v[26:29]
	v_mfma_f32_16x16x32_bf16 v[22:25], v[134:137], v[222:225], v[22:25]
	v_mfma_f32_16x16x32_bf16 v[18:21], v[134:137], v[226:229], v[18:21]
	global_load_dwordx4 v[134:137], v[250:251], off offset:448
	s_waitcnt vmcnt(11)
	v_mfma_f32_16x16x32_bf16 v[12:15], v[154:157], v[214:217], v[12:15]
	v_mfma_f32_16x16x32_bf16 v[8:11], v[154:157], v[218:221], v[8:11]
	v_mfma_f32_16x16x32_bf16 v[4:7], v[154:157], v[222:225], v[4:7]
	v_mfma_f32_16x16x32_bf16 v[0:3], v[154:157], v[226:229], v[0:3]
	global_load_dwordx4 v[154:157], v[148:149], off offset:448
	ds_read_b128 v[214:217], v16 offset:384
	ds_read_b128 v[218:221], v16 offset:8832
	ds_read_b128 v[222:225], v16 offset:17280
	ds_read_b128 v[226:229], v16 offset:25728
	s_waitcnt vmcnt(11) lgkmcnt(4)
	v_mfma_f32_16x16x32_bf16 v[66:69], v[172:175], v[230:233], v[66:69]
	v_mfma_f32_16x16x32_bf16 v[58:61], v[172:175], v[234:237], v[58:61]
	v_mfma_f32_16x16x32_bf16 v[54:57], v[172:175], v[238:241], v[54:57]
	v_mfma_f32_16x16x32_bf16 v[50:53], v[172:175], v[242:245], v[50:53]
	s_waitcnt vmcnt(10)
	v_mfma_f32_16x16x32_bf16 v[46:49], v[176:179], v[230:233], v[46:49]
	v_mfma_f32_16x16x32_bf16 v[42:45], v[176:179], v[234:237], v[42:45]
	v_mfma_f32_16x16x32_bf16 v[38:41], v[176:179], v[238:241], v[38:41]
	v_mfma_f32_16x16x32_bf16 v[34:37], v[176:179], v[242:245], v[34:37]
	s_waitcnt vmcnt(9)
	v_mfma_f32_16x16x32_bf16 v[30:33], v[180:183], v[230:233], v[30:33]
	v_mfma_f32_16x16x32_bf16 v[26:29], v[180:183], v[234:237], v[26:29]
	v_mfma_f32_16x16x32_bf16 v[22:25], v[180:183], v[238:241], v[22:25]
	v_mfma_f32_16x16x32_bf16 v[18:21], v[180:183], v[242:245], v[18:21]
	s_waitcnt vmcnt(8)
	v_mfma_f32_16x16x32_bf16 v[12:15], v[166:169], v[230:233], v[12:15]
	v_mfma_f32_16x16x32_bf16 v[8:11], v[166:169], v[234:237], v[8:11]
	v_mfma_f32_16x16x32_bf16 v[4:7], v[166:169], v[238:241], v[4:7]
	v_mfma_f32_16x16x32_bf16 v[0:3], v[166:169], v[242:245], v[0:3]
	ds_read_b128 v[230:233], v16 offset:448
	ds_read_b128 v[234:237], v16 offset:8896
	ds_read_b128 v[238:241], v16 offset:17344
	ds_read_b128 v[242:245], v16 offset:25792
	s_waitcnt vmcnt(7) lgkmcnt(4)
	v_mfma_f32_16x16x32_bf16 v[66:69], v[186:189], v[214:217], v[66:69]
	v_mfma_f32_16x16x32_bf16 v[58:61], v[186:189], v[218:221], v[58:61]
	v_mfma_f32_16x16x32_bf16 v[54:57], v[186:189], v[222:225], v[54:57]
	v_mfma_f32_16x16x32_bf16 v[50:53], v[186:189], v[226:229], v[50:53]
	s_waitcnt vmcnt(6)
	v_mfma_f32_16x16x32_bf16 v[46:49], v[190:193], v[214:217], v[46:49]
	v_mfma_f32_16x16x32_bf16 v[42:45], v[190:193], v[218:221], v[42:45]
	v_mfma_f32_16x16x32_bf16 v[38:41], v[190:193], v[222:225], v[38:41]
	v_mfma_f32_16x16x32_bf16 v[34:37], v[190:193], v[226:229], v[34:37]
	s_waitcnt vmcnt(5)
	v_mfma_f32_16x16x32_bf16 v[30:33], v[194:197], v[214:217], v[30:33]
	v_mfma_f32_16x16x32_bf16 v[26:29], v[194:197], v[218:221], v[26:29]
	v_mfma_f32_16x16x32_bf16 v[22:25], v[194:197], v[222:225], v[22:25]
	v_mfma_f32_16x16x32_bf16 v[18:21], v[194:197], v[226:229], v[18:21]
	s_waitcnt vmcnt(4)
	v_mfma_f32_16x16x32_bf16 v[12:15], v[198:201], v[214:217], v[12:15]
	v_mfma_f32_16x16x32_bf16 v[8:11], v[198:201], v[218:221], v[8:11]
	v_mfma_f32_16x16x32_bf16 v[4:7], v[198:201], v[222:225], v[4:7]
	v_mfma_f32_16x16x32_bf16 v[0:3], v[198:201], v[226:229], v[0:3]
	s_waitcnt vmcnt(3) lgkmcnt(0)
	v_mfma_f32_16x16x32_bf16 v[66:69], v[206:209], v[230:233], v[66:69]
	v_mfma_f32_16x16x32_bf16 v[58:61], v[206:209], v[234:237], v[58:61]
	v_mfma_f32_16x16x32_bf16 v[54:57], v[206:209], v[238:241], v[54:57]
	v_mfma_f32_16x16x32_bf16 v[50:53], v[206:209], v[242:245], v[50:53]
	s_waitcnt vmcnt(2)
	v_mfma_f32_16x16x32_bf16 v[46:49], v[246:249], v[230:233], v[46:49]
	v_mfma_f32_16x16x32_bf16 v[42:45], v[246:249], v[234:237], v[42:45]
	v_mfma_f32_16x16x32_bf16 v[38:41], v[246:249], v[238:241], v[38:41]
	v_mfma_f32_16x16x32_bf16 v[34:37], v[246:249], v[242:245], v[34:37]
	s_waitcnt vmcnt(1)
	v_mfma_f32_16x16x32_bf16 v[30:33], v[134:137], v[230:233], v[30:33]
	v_mfma_f32_16x16x32_bf16 v[26:29], v[134:137], v[234:237], v[26:29]
	v_mfma_f32_16x16x32_bf16 v[22:25], v[134:137], v[238:241], v[22:25]
	v_mfma_f32_16x16x32_bf16 v[18:21], v[134:137], v[242:245], v[18:21]
	s_waitcnt vmcnt(0)
	v_mfma_f32_16x16x32_bf16 v[12:15], v[154:157], v[230:233], v[12:15]
	v_mfma_f32_16x16x32_bf16 v[8:11], v[154:157], v[234:237], v[8:11]
	v_mfma_f32_16x16x32_bf16 v[4:7], v[154:157], v[238:241], v[4:7]
	v_mfma_f32_16x16x32_bf16 v[0:3], v[154:157], v[242:245], v[0:3]
	v_add_u32_e32 v16, 0x200, v16
	s_movk_i32 s0, 0x120
	s_movk_i32 s40, 0xe0
	s_branch .LBB0_867

; #define LAS __attribute__((address_space(3)))
; __device__ __forceinline__ unsigned pk2(float lo, float hi) { return pg8::cvt_pk_bf16(lo, hi); }
; __device__ __forceinline__ f32x4 mma16(bf16x8 a, bf16x8 b, f32x4 c) { return __builtin_amdgcn_mfma_f32_16x16x32_bf16(a, b, c, 0, 0, 0); }
; #define BSYNC() do { asm volatile("s_waitcnt vmcnt(0) lgkmcnt(0)" ::: "memory"); __syncthreads(); } while (0)
; template <int TY> __device__ __forceinline__ void mc_item(const Params& p, ldsp lds, int item) {
;     ...
;     for (int j = 0; j <= jc; ++j) { const size_t rowj = (size_t)b * 2048 + (sc * NB + j) * 64;
;         if constexpr (TY == 2) { st_rows<256>(KTs, PQ, kr, tid); st_T<512>(VTs, 72, vr, wave, lane); }
;         else { stage_rows<DK>(KTs, PQ, (const bf16_t*)(p.ws + WS_KT) + rowj * 768 + ecol, 768, tid);
;                stage_T<DV>(VTs, 72, Pb + rowj * PP + voff, PP, wave, lane); }
;         if constexpr (TY == 2) { __syncthreads(); if (j < jc) { const size_t rown = rowj + 64; ld_rows<256>(kr, Pb + rown * NO + O_K + h * 256, NO, tid); ld_T<512>(vr, Pb + rown * NO + voff, NO, wave, lane); } }
;         else BSYNC();
;         { f32x4 c0 = (f32x4){0.f, 0.f, 0.f, 0.f}, c1 = c0;
; #pragma unroll
;           for (int ks = 0; ks < DK / 32; ++ks) { const bf16x8 bq = ldfrag(QX, (16 * tt + l15) * PQ + 32 * ks + 8 * q4);
;               c0 = mma16(ldfrag(KTs, (16 * (2 * sp) + l15) * PQ + 32 * ks + 8 * q4), bq, c0);
;               c1 = mma16(ldfrag(KTs, (16 * (2 * sp + 1) + l15) * PQ + 32 * ks + 8 * q4), bq, c1); }
;           const int t = 16 * tt + l15;
;           const int tl = (j == jc) ? t : 4096;
; #pragma unroll
;           for (int jj = 0; jj < 4; ++jj) { if (32 * sp + 4 * q4 + jj > tl) c0[jj] = 0.f; if (32 * sp + 16 + 4 * q4 + jj > tl) c1[jj] = 0.f; }
;           u32x2 w; w.x = pk2(c0[0], c0[1]); w.y = pk2(c0[2], c0[3]); *(LAS u32x2*)(Pm + (size_t)(t * 72 + 32 * sp + 4 * q4) * 2) = w;
;           w.x = pk2(c1[0], c1[1]); w.y = pk2(c1[2], c1[3]); *(LAS u32x2*)(Pm + (size_t)(t * 72 + 32 * sp + 16 + 4 * q4) * 2) = w; }
;         if constexpr (TY == 2) __syncthreads(); else BSYNC();
.LBB0_883:
	v_add_u32_e32 v16, v206, v203
	s_waitcnt vmcnt(11)
	ds_write_b128 v16, v[130:133] offset:33792
	v_add_u32_e32 v16, v207, v204
	s_waitcnt vmcnt(10)
	ds_write_b128 v16, v[126:129] offset:33792
	v_add_u32_e32 v16, v208, v205
	s_waitcnt vmcnt(9)
	ds_write_b128 v16, v[122:125] offset:33792
	v_add_u32_e32 v16, v210, v209
	s_waitcnt vmcnt(8)
	ds_write_b128 v16, v[118:121] offset:33792
	s_waitcnt vmcnt(7)
	ds_write_b16 v162, v26
	ds_write_b16_d16_hi v162, v26 offset:144
	ds_write_b16 v162, v27 offset:288
	ds_write_b16_d16_hi v162, v27 offset:432
	ds_write_b16 v162, v28 offset:576
	ds_write_b16_d16_hi v162, v28 offset:720
	ds_write_b16 v162, v29 offset:864
	ds_write_b16_d16_hi v162, v29 offset:1008
	s_waitcnt vmcnt(6)
	ds_write_b16 v162, v22 offset:9216
	ds_write_b16_d16_hi v162, v22 offset:9360
	ds_write_b16 v162, v23 offset:9504
	ds_write_b16_d16_hi v162, v23 offset:9648
	ds_write_b16 v162, v24 offset:9792
	ds_write_b16_d16_hi v162, v24 offset:9936
	ds_write_b16 v162, v25 offset:10080
	ds_write_b16_d16_hi v162, v25 offset:10224
	s_waitcnt vmcnt(5)
	ds_write_b16 v162, v18 offset:18432
	ds_write_b16_d16_hi v162, v18 offset:18576
	ds_write_b16 v162, v19 offset:18720
	ds_write_b16_d16_hi v162, v19 offset:18864
	ds_write_b16 v162, v20 offset:19008
	ds_write_b16_d16_hi v162, v20 offset:19152
	ds_write_b16 v162, v21 offset:19296
	ds_write_b16_d16_hi v162, v21 offset:19440
	s_waitcnt vmcnt(4)
	ds_write_b16 v162, v12 offset:27648
	ds_write_b16_d16_hi v162, v12 offset:27792
	ds_write_b16 v162, v13 offset:27936
	ds_write_b16_d16_hi v162, v13 offset:28080
	ds_write_b16 v162, v14 offset:28224
	ds_write_b16_d16_hi v162, v14 offset:28368
	ds_write_b16 v162, v15 offset:28512
	ds_write_b16_d16_hi v162, v15 offset:28656
	s_waitcnt vmcnt(3)
	ds_write_b16 v162, v8 offset:36864
	ds_write_b16_d16_hi v162, v8 offset:37008
	ds_write_b16 v162, v9 offset:37152
	ds_write_b16_d16_hi v162, v9 offset:37296
	ds_write_b16 v162, v10 offset:37440
	ds_write_b16_d16_hi v162, v10 offset:37584
	ds_write_b16 v162, v11 offset:37728
	ds_write_b16_d16_hi v162, v11 offset:37872
	s_waitcnt vmcnt(2)
	ds_write_b16 v162, v4 offset:46080
	ds_write_b16_d16_hi v162, v4 offset:46224
	ds_write_b16 v162, v5 offset:46368
	ds_write_b16_d16_hi v162, v5 offset:46512
	ds_write_b16 v162, v6 offset:46656
	ds_write_b16_d16_hi v162, v6 offset:46800
	ds_write_b16 v162, v7 offset:46944
	ds_write_b16_d16_hi v162, v7 offset:47088
	s_waitcnt vmcnt(1)
	ds_write_b16 v162, v0 offset:55296
	ds_write_b16_d16_hi v162, v0 offset:55440
	ds_write_b16 v162, v1 offset:55584
	ds_write_b16_d16_hi v162, v1 offset:55728
	ds_write_b16 v162, v2 offset:55872
	ds_write_b16_d16_hi v162, v2 offset:56016
	ds_write_b16 v162, v3 offset:56160
	ds_write_b16_d16_hi v162, v3 offset:56304
	s_waitcnt vmcnt(0)
	ds_write_b16 v162, v98 offset:64512
	ds_write_b16_d16_hi v162, v98 offset:64656
	ds_write_b16 v162, v99 offset:64800
	ds_write_b16_d16_hi v162, v99 offset:64944
	ds_write_b16 v162, v100 offset:65088
	ds_write_b16_d16_hi v162, v100 offset:65232
	ds_write_b16 v162, v101 offset:65376
	ds_write_b16_d16_hi v162, v101 offset:65520
	v_add_u32_e32 v16, 0, v217
	s_waitcnt lgkmcnt(0)
	s_barrier
	ds_read_b128 v[0:3], v16 offset:33792
	v_add_u32_e32 v30, 0, v163
	ds_read_b128 v[4:7], v30
	ds_read_b128 v[8:11], v30 offset:64
	ds_read_b128 v[12:15], v16 offset:33856
	s_waitcnt lgkmcnt(2)
	v_mfma_f32_16x16x32_bf16 v[0:3], v[0:3], v[4:7], 0
	v_add_u32_e32 v31, 0, v216
	ds_read_b128 v[18:21], v31 offset:33792
	ds_read_b128 v[22:25], v31 offset:33856
	v_cmp_gt_i32_e32 vcc, v157, v155
	s_waitcnt lgkmcnt(2)
	v_mfma_f32_16x16x32_bf16 v[0:3], v[12:15], v[8:11], v[0:3]
	ds_read_b128 v[12:15], v16 offset:33920
	v_or_b32_e32 v146, 16, v150
	s_cmp_gt_u32 s40, 3
	s_waitcnt lgkmcnt(2)
	v_mfma_f32_16x16x32_bf16 v[4:7], v[18:21], v[4:7], 0
	s_mov_b64 s[0:1], -1
	s_waitcnt lgkmcnt(1)
	v_mfma_f32_16x16x32_bf16 v[4:7], v[22:25], v[8:11], v[4:7]
	ds_read_b128 v[8:11], v30 offset:128
	ds_read_b128 v[18:21], v30 offset:192
	ds_read_b128 v[22:25], v16 offset:33984
	s_waitcnt lgkmcnt(2)
	v_mfma_f32_16x16x32_bf16 v[0:3], v[12:15], v[8:11], v[0:3]
	ds_read_b128 v[12:15], v31 offset:33920
	ds_read_b128 v[26:29], v31 offset:33984
	s_waitcnt lgkmcnt(1)
	v_mfma_f32_16x16x32_bf16 v[4:7], v[12:15], v[8:11], v[4:7]
	ds_read_b128 v[8:11], v16 offset:34048
	v_mfma_f32_16x16x32_bf16 v[0:3], v[22:25], v[18:21], v[0:3]
	s_waitcnt lgkmcnt(1)
	v_mfma_f32_16x16x32_bf16 v[4:7], v[26:29], v[18:21], v[4:7]
	ds_read_b128 v[12:15], v30 offset:256
	ds_read_b128 v[18:21], v30 offset:320
	ds_read_b128 v[22:25], v16 offset:34112
	s_waitcnt lgkmcnt(2)
	v_mfma_f32_16x16x32_bf16 v[0:3], v[8:11], v[12:15], v[0:3]
	ds_read_b128 v[8:11], v31 offset:34048
	ds_read_b128 v[26:29], v31 offset:34112
	s_waitcnt lgkmcnt(1)
	v_mfma_f32_16x16x32_bf16 v[4:7], v[8:11], v[12:15], v[4:7]
	ds_read_b128 v[8:11], v16 offset:34176
	v_mfma_f32_16x16x32_bf16 v[0:3], v[22:25], v[18:21], v[0:3]
	s_waitcnt lgkmcnt(1)
	v_mfma_f32_16x16x32_bf16 v[4:7], v[26:29], v[18:21], v[4:7]
	ds_read_b128 v[12:15], v30 offset:384
	ds_read_b128 v[18:21], v30 offset:448
	ds_read_b128 v[22:25], v16 offset:34240
	v_mad_u32_u24 v16, v146, s9, v154
	s_waitcnt lgkmcnt(2)
	v_mfma_f32_16x16x32_bf16 v[0:3], v[8:11], v[12:15], v[0:3]
	ds_read_b128 v[8:11], v31 offset:34176
	ds_read_b128 v[26:29], v31 offset:34240
	s_waitcnt lgkmcnt(1)
	v_mfma_f32_16x16x32_bf16 v[4:7], v[8:11], v[12:15], v[4:7]
	v_mov_b32_e32 v8, s41
	v_add_u32_e32 v12, v139, v202
	v_mfma_f32_16x16x32_bf16 v[0:3], v[22:25], v[18:21], v[0:3]
	s_waitcnt lgkmcnt(0)
	v_mfma_f32_16x16x32_bf16 v[4:7], v[26:29], v[18:21], v[4:7]
	s_nop 5
	v_cndmask_b32_e32 v9, v0, v8, vcc
	v_cmp_gt_i32_e32 vcc, v215, v155
	s_nop 1
	v_cndmask_b32_e32 v4, v4, v8, vcc
	v_cmp_lt_i32_e32 vcc, v157, v155
	v_or_b32_e32 v8, 2, v157
	s_nop 0
	v_cndmask_b32_e32 v0, v9, v0, vcc
	v_cndmask_b32_e32 v1, 0, v1, vcc
	v_cmp_le_i32_e32 vcc, v214, v155
	v_cvt_pk_bf16_f32 v0, v0, v1
	s_nop 1
	v_cndmask_b32_e32 v5, 0, v5, vcc
	v_cmp_le_i32_e32 vcc, v8, v155
	v_add_u32_e32 v8, v154, v201
	s_nop 0
	v_cndmask_b32_e32 v2, 0, v2, vcc
	v_cmp_le_i32_e32 vcc, v211, v155
	s_nop 1
	v_cndmask_b32_e32 v6, 0, v6, vcc
	v_cmp_le_i32_e32 vcc, v212, v155
	s_nop 1
	v_cndmask_b32_e32 v3, 0, v3, vcc
	v_cvt_pk_bf16_f32 v1, v2, v3
	v_add_u32_e32 v2, 0, v156
	v_cmp_le_i32_e32 vcc, v213, v155
	v_add_u32_e32 v2, 0x22800, v2
	ds_write_b64 v2, v[0:1]
	v_cndmask_b32_e32 v7, 0, v7, vcc
	v_cvt_pk_bf16_f32 v0, v4, v5
	v_cvt_pk_bf16_f32 v1, v6, v7
	ds_write_b64 v2, v[0:1] offset:32
	s_waitcnt lgkmcnt(0)
	s_barrier
; __device__ __forceinline__ f32x4 mma16(bf16x8 a, bf16x8 b, f32x4 c) { return __builtin_amdgcn_mfma_f32_16x16x32_bf16(a, b, c, 0, 0, 0); }
; #define BSYNC() do { asm volatile("s_waitcnt vmcnt(0) lgkmcnt(0)" ::: "memory"); __syncthreads(); } while (0)
; template <int TY> __device__ __forceinline__ void mc_item(const Params& p, ldsp lds, int item) {
;     ...
;         if constexpr (TY == 2) __syncthreads(); else BSYNC();
; #pragma unroll
;         for (int ks = 0; ks < 2; ++ks) { bf16x8 pb[4];
; #pragma unroll
;             for (int tk = 0; tk < 4; ++tk) pb[tk] = ldfrag(Pm, (16 * tk + l15) * 72 + 32 * ks + 8 * q4);
; #pragma unroll
;             for (int ei = 0; ei < ET; ++ei) { const bf16x8 va = ldfrag(VTs, (16 * (wave * ET + ei) + l15) * 72 + 32 * ks + 8 * q4);
; #pragma unroll
;                 for (int tk = 0; tk < 4; ++tk) acc[ei][tk] = mma16(va, pb[tk], acc[ei][tk]); } }
;         if constexpr (TY == 2) __syncthreads(); else BSYNC(); }
;     if ((TY == 2 ? sc : c) != 0) { const bf16_t* STp = (TY == 2) ? (const bf16_t*)(p.ws + WS_ST) + ((size_t)bh * 8 + sc) * 512 * 256
;                                     : (const bf16_t*)(p.ws + WS_ST + (TY ? ST_HGRN : 0)) + ((size_t)bh * 32 + c) * 128 * DK;
;       ldsp QS = (TY == 2) ? QX : QH2;
;       bf16x8 sa[ET], sn[ET];
; #pragma unroll
;       for (int ei = 0; ei < ET; ++ei) sa[ei] = *(const bf16x8*)(STp + (size_t)(16 * (wave * ET + ei) + l15) * DK + 8 * q4);
; #pragma unroll 1
;       for (int ks = 0; ks < DK / 32; ++ks) { bf16x8 qb[4];
;           const int kn = (ks + 1 < DK / 32) ? ks + 1 : ks;
; #pragma unroll
;           for (int ei = 0; ei < ET; ++ei) sn[ei] = *(const bf16x8*)(STp + (size_t)(16 * (wave * ET + ei) + l15) * DK + 32 * kn + 8 * q4);
; #pragma unroll
;           for (int tk = 0; tk < 4; ++tk) qb[tk] = ldfrag(QS, (16 * tk + l15) * PQ + 32 * ks + 8 * q4);
	ds_read_b128 v[0:3], v12
	ds_read_b128 v[4:7], v8
	ds_read_b128 v[8:11], v8 offset:64
	ds_read_b128 v[12:15], v12 offset:64
	ds_read_b128 v[22:25], v16
	ds_read_b128 v[26:29], v16 offset:64
	ds_read_b128 v[34:37], v16 offset:2304
	ds_read_b128 v[38:41], v16 offset:2368
	s_waitcnt lgkmcnt(1)
	v_mfma_f32_16x16x32_bf16 v[46:49], v[0:3], v[34:37], v[50:53]
	s_nop 2
	ds_read_b128 v[50:53], v16 offset:4608
	ds_read_b128 v[54:57], v16 offset:4672
	v_add_u32_e32 v16, v139, v160
	v_mfma_f32_16x16x32_bf16 v[18:21], v[0:3], v[4:7], v[62:65]
	v_mfma_f32_16x16x32_bf16 v[30:33], v[0:3], v[22:25], v[58:61]
	s_waitcnt lgkmcnt(1)
	v_mfma_f32_16x16x32_bf16 v[0:3], v[0:3], v[50:53], v[42:45]
	s_nop 2
	ds_read_b128 v[42:45], v16
	ds_read_b128 v[58:61], v16 offset:64
	v_add_u32_e32 v16, v139, v159
	ds_read_b128 v[62:65], v16
	ds_read_b128 v[122:125], v16 offset:64
	v_add_u32_e32 v16, v139, v158
	s_waitcnt lgkmcnt(1)
	v_mfma_f32_16x16x32_bf16 v[126:129], v[62:65], v[4:7], v[82:85]
	v_mfma_f32_16x16x32_bf16 v[130:133], v[62:65], v[22:25], v[86:89]
	v_mfma_f32_16x16x32_bf16 v[134:137], v[62:65], v[34:37], v[90:93]
	v_mfma_f32_16x16x32_bf16 v[140:143], v[62:65], v[50:53], v[94:97]
	ds_read_b128 v[62:65], v16
	ds_read_b128 v[154:157], v16 offset:64
	s_waitcnt lgkmcnt(0)
	s_barrier
	v_mfma_f32_16x16x32_bf16 v[66:69], v[42:45], v[4:7], v[66:69]
	v_mfma_f32_16x16x32_bf16 v[98:101], v[42:45], v[22:25], v[70:73]
	v_mfma_f32_16x16x32_bf16 v[118:121], v[42:45], v[34:37], v[74:77]
	v_mfma_f32_16x16x32_bf16 v[42:45], v[42:45], v[50:53], v[78:81]
	v_mfma_f32_16x16x32_bf16 v[4:7], v[62:65], v[4:7], v[102:105]
	v_mfma_f32_16x16x32_bf16 v[22:25], v[62:65], v[22:25], v[106:109]
	v_mfma_f32_16x16x32_bf16 v[34:37], v[62:65], v[34:37], v[110:113]
	v_mfma_f32_16x16x32_bf16 v[50:53], v[62:65], v[50:53], v[114:117]
	v_mfma_f32_16x16x32_bf16 v[62:65], v[12:15], v[8:11], v[18:21]
	v_mfma_f32_16x16x32_bf16 v[70:73], v[12:15], v[26:29], v[30:33]
	v_mfma_f32_16x16x32_bf16 v[74:77], v[12:15], v[38:41], v[46:49]
	v_mfma_f32_16x16x32_bf16 v[110:113], v[12:15], v[54:57], v[0:3]
	v_mfma_f32_16x16x32_bf16 v[78:81], v[58:61], v[8:11], v[66:69]
	v_mfma_f32_16x16x32_bf16 v[82:85], v[58:61], v[26:29], v[98:101]
	v_mfma_f32_16x16x32_bf16 v[86:89], v[58:61], v[38:41], v[118:121]
	v_mfma_f32_16x16x32_bf16 v[90:93], v[58:61], v[54:57], v[42:45]
	v_mfma_f32_16x16x32_bf16 v[94:97], v[122:125], v[8:11], v[126:129]
	v_mfma_f32_16x16x32_bf16 v[98:101], v[122:125], v[26:29], v[130:133]
	v_mfma_f32_16x16x32_bf16 v[102:105], v[122:125], v[38:41], v[134:137]
	v_mfma_f32_16x16x32_bf16 v[106:109], v[122:125], v[54:57], v[140:143]
	v_mfma_f32_16x16x32_bf16 v[114:117], v[154:157], v[8:11], v[4:7]
	v_mfma_f32_16x16x32_bf16 v[118:121], v[154:157], v[26:29], v[22:25]
	v_mfma_f32_16x16x32_bf16 v[122:125], v[154:157], v[38:41], v[34:37]
	v_mfma_f32_16x16x32_bf16 v[126:129], v[154:157], v[54:57], v[50:53]
	s_cbranch_scc0 .LBB0_887
	s_ashr_i32 s9, s8, 31
	s_lshl_b64 s[0:1], s[8:9], 21
	v_readlane_b32 s8, v254, 9
	v_readlane_b32 s9, v254, 10
	s_add_u32 s0, s8, s0
	s_addc_u32 s1, s9, s1
	s_lshl_b32 s8, s40, 16
	s_and_b32 s8, s8, 0x1c0000
	s_add_u32 s0, s0, s8
	s_addc_u32 s1, s1, 0
	s_and_b32 s9, s60, 0xffffffc0
	v_or_b32_e32 v0, s9, v150
	v_or_b32_e32 v2, 16, v0
	v_ashrrev_i32_e32 v1, 31, v0
	v_ashrrev_i32_e32 v3, 31, v2
	v_lshlrev_b32_e32 v16, 1, v138
	v_lshlrev_b64 v[132:133], 9, v[0:1]
	v_lshlrev_b64 v[138:139], 9, v[2:3]
	v_or_b32_e32 v2, 32, v0
	v_or_b32_e32 v0, 48, v0
	v_ashrrev_i32_e32 v1, 31, v0
	v_ashrrev_i32_e32 v3, 31, v2
	v_lshlrev_b64 v[142:143], 9, v[0:1]
	v_mul_u32_u24_e32 v0, 0x210, v150
	v_lshl_add_u64 v[130:131], s[0:1], 0, v[16:17]
	v_lshlrev_b64 v[140:141], 9, v[2:3]
	v_add3_u32 v16, v0, v153, 0
	v_lshl_add_u64 v[202:203], v[130:131], 0, v[132:133]
	v_lshl_add_u64 v[210:211], v[130:131], 0, v[138:139]
	v_lshl_add_u64 v[250:251], v[130:131], 0, v[140:141]
	v_lshl_add_u64 v[148:149], v[130:131], 0, v[142:143]
	global_load_dwordx4 v[186:189], v[202:203], off
	global_load_dwordx4 v[190:193], v[210:211], off
	global_load_dwordx4 v[194:197], v[250:251], off
	global_load_dwordx4 v[198:201], v[148:149], off
	global_load_dwordx4 v[206:209], v[202:203], off offset:64
	global_load_dwordx4 v[246:249], v[210:211], off offset:64
	global_load_dwordx4 v[134:137], v[250:251], off offset:64
	global_load_dwordx4 v[154:157], v[148:149], off offset:64
	global_load_dwordx4 v[172:175], v[202:203], off offset:128
	global_load_dwordx4 v[176:179], v[210:211], off offset:128
	global_load_dwordx4 v[180:183], v[250:251], off offset:128
	global_load_dwordx4 v[166:169], v[148:149], off offset:128
	ds_read_b128 v[214:217], v16
	ds_read_b128 v[218:221], v16 offset:8448
	ds_read_b128 v[222:225], v16 offset:16896
	ds_read_b128 v[226:229], v16 offset:25344
	v_mov_b64_e32 v[50:51], v[110:111]
	v_mov_b64_e32 v[54:55], v[74:75]
	v_mov_b64_e32 v[58:59], v[70:71]
	v_mov_b64_e32 v[68:69], v[64:65]
	v_mov_b64_e32 v[46:47], v[78:79]
	v_mov_b64_e32 v[42:43], v[82:83]
	v_mov_b64_e32 v[38:39], v[86:87]
	v_mov_b64_e32 v[34:35], v[90:91]
	v_mov_b64_e32 v[30:31], v[94:95]
	v_mov_b64_e32 v[26:27], v[98:99]
	v_mov_b64_e32 v[22:23], v[102:103]
	v_mov_b64_e32 v[18:19], v[106:107]
	v_mov_b64_e32 v[12:13], v[114:115]
	v_mov_b64_e32 v[8:9], v[118:119]
	v_mov_b64_e32 v[4:5], v[122:123]
	v_mov_b64_e32 v[0:1], v[126:127]
	s_mov_b32 s0, 32
	v_mov_b64_e32 v[52:53], v[112:113]
	v_mov_b64_e32 v[56:57], v[76:77]
	v_mov_b64_e32 v[60:61], v[72:73]
	v_mov_b64_e32 v[66:67], v[62:63]
	v_mov_b64_e32 v[144:145], v[130:131]
	v_mov_b64_e32 v[48:49], v[80:81]
	v_mov_b64_e32 v[44:45], v[84:85]
	v_mov_b64_e32 v[40:41], v[88:89]
	v_mov_b64_e32 v[36:37], v[92:93]
	v_mov_b64_e32 v[32:33], v[96:97]
	v_mov_b64_e32 v[28:29], v[100:101]
	v_mov_b64_e32 v[24:25], v[104:105]
	v_mov_b64_e32 v[20:21], v[108:109]
	v_mov_b64_e32 v[14:15], v[116:117]
	v_mov_b64_e32 v[10:11], v[120:121]
	v_mov_b64_e32 v[6:7], v[124:125]
	v_mov_b64_e32 v[2:3], v[128:129]
; __device__ __forceinline__ f32x4 mma16(bf16x8 a, bf16x8 b, f32x4 c) { return __builtin_amdgcn_mfma_f32_16x16x32_bf16(a, b, c, 0, 0, 0); }
; template <int TY> __device__ __forceinline__ void mc_item(const Params& p, ldsp lds, int item) {
;     ...
; #pragma unroll 1
;       for (int ks = 0; ks < DK / 32; ++ks) { bf16x8 qb[4];
;           const int kn = (ks + 1 < DK / 32) ? ks + 1 : ks;
; #pragma unroll
;           for (int ei = 0; ei < ET; ++ei) sn[ei] = *(const bf16x8*)(STp + (size_t)(16 * (wave * ET + ei) + l15) * DK + 32 * kn + 8 * q4);
; #pragma unroll
;           for (int tk = 0; tk < 4; ++tk) qb[tk] = ldfrag(QS, (16 * tk + l15) * PQ + 32 * ks + 8 * q4);
; #pragma unroll
;           for (int ei = 0; ei < ET; ++ei) {
; #pragma unroll
;               for (int tk = 0; tk < 4; ++tk) acc[ei][tk] = mma16(sa[ei], qb[tk], acc[ei][tk]); }
; #pragma unroll
;           for (int ei = 0; ei < ET; ++ei) sa[ei] = sn[ei]; } }
.LBB0_885:
	ds_read_b128 v[230:233], v16 offset:64
	ds_read_b128 v[234:237], v16 offset:8512
	ds_read_b128 v[238:241], v16 offset:16960
	ds_read_b128 v[242:245], v16 offset:25408
	s_waitcnt vmcnt(11) lgkmcnt(4)
	v_mfma_f32_16x16x32_bf16 v[66:69], v[186:189], v[214:217], v[66:69]
	v_mfma_f32_16x16x32_bf16 v[58:61], v[186:189], v[218:221], v[58:61]
	v_mfma_f32_16x16x32_bf16 v[54:57], v[186:189], v[222:225], v[54:57]
	v_mfma_f32_16x16x32_bf16 v[50:53], v[186:189], v[226:229], v[50:53]
	global_load_dwordx4 v[186:189], v[202:203], off offset:192
	s_waitcnt vmcnt(11)
	v_mfma_f32_16x16x32_bf16 v[46:49], v[190:193], v[214:217], v[46:49]
	v_mfma_f32_16x16x32_bf16 v[42:45], v[190:193], v[218:221], v[42:45]
	v_mfma_f32_16x16x32_bf16 v[38:41], v[190:193], v[222:225], v[38:41]
	v_mfma_f32_16x16x32_bf16 v[34:37], v[190:193], v[226:229], v[34:37]
	global_load_dwordx4 v[190:193], v[210:211], off offset:192
	s_waitcnt vmcnt(11)
	v_mfma_f32_16x16x32_bf16 v[30:33], v[194:197], v[214:217], v[30:33]
	v_mfma_f32_16x16x32_bf16 v[26:29], v[194:197], v[218:221], v[26:29]
	v_mfma_f32_16x16x32_bf16 v[22:25], v[194:197], v[222:225], v[22:25]
	v_mfma_f32_16x16x32_bf16 v[18:21], v[194:197], v[226:229], v[18:21]
	global_load_dwordx4 v[194:197], v[250:251], off offset:192
	s_waitcnt vmcnt(11)
	v_mfma_f32_16x16x32_bf16 v[12:15], v[198:201], v[214:217], v[12:15]
	v_mfma_f32_16x16x32_bf16 v[8:11], v[198:201], v[218:221], v[8:11]
	v_mfma_f32_16x16x32_bf16 v[4:7], v[198:201], v[222:225], v[4:7]
	v_mfma_f32_16x16x32_bf16 v[0:3], v[198:201], v[226:229], v[0:3]
	global_load_dwordx4 v[198:201], v[148:149], off offset:192
	ds_read_b128 v[214:217], v16 offset:128
	ds_read_b128 v[218:221], v16 offset:8576
	ds_read_b128 v[222:225], v16 offset:17024
	ds_read_b128 v[226:229], v16 offset:25472
	s_waitcnt vmcnt(11) lgkmcnt(4)
	v_mfma_f32_16x16x32_bf16 v[66:69], v[206:209], v[230:233], v[66:69]
	v_mfma_f32_16x16x32_bf16 v[58:61], v[206:209], v[234:237], v[58:61]
	v_mfma_f32_16x16x32_bf16 v[54:57], v[206:209], v[238:241], v[54:57]
	v_mfma_f32_16x16x32_bf16 v[50:53], v[206:209], v[242:245], v[50:53]
	global_load_dwordx4 v[206:209], v[202:203], off offset:256
	s_waitcnt vmcnt(11)
	v_mfma_f32_16x16x32_bf16 v[46:49], v[246:249], v[230:233], v[46:49]
	v_mfma_f32_16x16x32_bf16 v[42:45], v[246:249], v[234:237], v[42:45]
	v_mfma_f32_16x16x32_bf16 v[38:41], v[246:249], v[238:241], v[38:41]
	v_mfma_f32_16x16x32_bf16 v[34:37], v[246:249], v[242:245], v[34:37]
	global_load_dwordx4 v[246:249], v[210:211], off offset:256
	s_waitcnt vmcnt(11)
	v_mfma_f32_16x16x32_bf16 v[30:33], v[134:137], v[230:233], v[30:33]
	v_mfma_f32_16x16x32_bf16 v[26:29], v[134:137], v[234:237], v[26:29]
	v_mfma_f32_16x16x32_bf16 v[22:25], v[134:137], v[238:241], v[22:25]
	v_mfma_f32_16x16x32_bf16 v[18:21], v[134:137], v[242:245], v[18:21]
	global_load_dwordx4 v[134:137], v[250:251], off offset:256
	s_waitcnt vmcnt(11)
	v_mfma_f32_16x16x32_bf16 v[12:15], v[154:157], v[230:233], v[12:15]
	v_mfma_f32_16x16x32_bf16 v[8:11], v[154:157], v[234:237], v[8:11]
	v_mfma_f32_16x16x32_bf16 v[4:7], v[154:157], v[238:241], v[4:7]
	v_mfma_f32_16x16x32_bf16 v[0:3], v[154:157], v[242:245], v[0:3]
	global_load_dwordx4 v[154:157], v[148:149], off offset:256
	ds_read_b128 v[230:233], v16 offset:192
	ds_read_b128 v[234:237], v16 offset:8640
	ds_read_b128 v[238:241], v16 offset:17088
	ds_read_b128 v[242:245], v16 offset:25536
	s_waitcnt vmcnt(11) lgkmcnt(4)
	v_mfma_f32_16x16x32_bf16 v[66:69], v[172:175], v[214:217], v[66:69]
	v_mfma_f32_16x16x32_bf16 v[58:61], v[172:175], v[218:221], v[58:61]
	v_mfma_f32_16x16x32_bf16 v[54:57], v[172:175], v[222:225], v[54:57]
	v_mfma_f32_16x16x32_bf16 v[50:53], v[172:175], v[226:229], v[50:53]
	global_load_dwordx4 v[172:175], v[202:203], off offset:320
	s_waitcnt vmcnt(11)
	v_mfma_f32_16x16x32_bf16 v[46:49], v[176:179], v[214:217], v[46:49]
	v_mfma_f32_16x16x32_bf16 v[42:45], v[176:179], v[218:221], v[42:45]
	v_mfma_f32_16x16x32_bf16 v[38:41], v[176:179], v[222:225], v[38:41]
	v_mfma_f32_16x16x32_bf16 v[34:37], v[176:179], v[226:229], v[34:37]
	global_load_dwordx4 v[176:179], v[210:211], off offset:320
	s_waitcnt vmcnt(11)
	v_mfma_f32_16x16x32_bf16 v[30:33], v[180:183], v[214:217], v[30:33]
	v_mfma_f32_16x16x32_bf16 v[26:29], v[180:183], v[218:221], v[26:29]
	v_mfma_f32_16x16x32_bf16 v[22:25], v[180:183], v[222:225], v[22:25]
	v_mfma_f32_16x16x32_bf16 v[18:21], v[180:183], v[226:229], v[18:21]
	global_load_dwordx4 v[180:183], v[250:251], off offset:320
	s_waitcnt vmcnt(11)
	v_mfma_f32_16x16x32_bf16 v[12:15], v[166:169], v[214:217], v[12:15]
	v_mfma_f32_16x16x32_bf16 v[8:11], v[166:169], v[218:221], v[8:11]
	v_mfma_f32_16x16x32_bf16 v[4:7], v[166:169], v[222:225], v[4:7]
	v_mfma_f32_16x16x32_bf16 v[0:3], v[166:169], v[226:229], v[0:3]
	global_load_dwordx4 v[166:169], v[148:149], off offset:320
	ds_read_b128 v[214:217], v16 offset:256
	ds_read_b128 v[218:221], v16 offset:8704
	ds_read_b128 v[222:225], v16 offset:17152
	ds_read_b128 v[226:229], v16 offset:25600
	s_waitcnt vmcnt(11) lgkmcnt(4)
	v_mfma_f32_16x16x32_bf16 v[66:69], v[186:189], v[230:233], v[66:69]
	v_mfma_f32_16x16x32_bf16 v[58:61], v[186:189], v[234:237], v[58:61]
	v_mfma_f32_16x16x32_bf16 v[54:57], v[186:189], v[238:241], v[54:57]
	v_mfma_f32_16x16x32_bf16 v[50:53], v[186:189], v[242:245], v[50:53]
	global_load_dwordx4 v[186:189], v[202:203], off offset:384
	s_waitcnt vmcnt(11)
	v_mfma_f32_16x16x32_bf16 v[46:49], v[190:193], v[230:233], v[46:49]
	v_mfma_f32_16x16x32_bf16 v[42:45], v[190:193], v[234:237], v[42:45]
	v_mfma_f32_16x16x32_bf16 v[38:41], v[190:193], v[238:241], v[38:41]
	v_mfma_f32_16x16x32_bf16 v[34:37], v[190:193], v[242:245], v[34:37]
	global_load_dwordx4 v[190:193], v[210:211], off offset:384
	s_waitcnt vmcnt(11)
; __device__ __forceinline__ f32x4 mma16(bf16x8 a, bf16x8 b, f32x4 c) { return __builtin_amdgcn_mfma_f32_16x16x32_bf16(a, b, c, 0, 0, 0); }
; template <int TY> __device__ __forceinline__ void mc_item(const Params& p, ldsp lds, int item) {
;     ...
; #pragma unroll 1
;       for (int ks = 0; ks < DK / 32; ++ks) { bf16x8 qb[4];
;           const int kn = (ks + 1 < DK / 32) ? ks + 1 : ks;
; #pragma unroll
;           for (int ei = 0; ei < ET; ++ei) sn[ei] = *(const bf16x8*)(STp + (size_t)(16 * (wave * ET + ei) + l15) * DK + 32 * kn + 8 * q4);
; #pragma unroll
;           for (int tk = 0; tk < 4; ++tk) qb[tk] = ldfrag(QS, (16 * tk + l15) * PQ + 32 * ks + 8 * q4);
; #pragma unroll
;           for (int ei = 0; ei < ET; ++ei) {
; #pragma unroll
;               for (int tk = 0; tk < 4; ++tk) acc[ei][tk] = mma16(sa[ei], qb[tk], acc[ei][tk]); }
; #pragma unroll
;           for (int ei = 0; ei < ET; ++ei) sa[ei] = sn[ei]; } }
	v_mfma_f32_16x16x32_bf16 v[30:33], v[194:197], v[230:233], v[30:33]
	v_mfma_f32_16x16x32_bf16 v[26:29], v[194:197], v[234:237], v[26:29]
	v_mfma_f32_16x16x32_bf16 v[22:25], v[194:197], v[238:241], v[22:25]
	v_mfma_f32_16x16x32_bf16 v[18:21], v[194:197], v[242:245], v[18:21]
	global_load_dwordx4 v[194:197], v[250:251], off offset:384
	s_waitcnt vmcnt(11)
	v_mfma_f32_16x16x32_bf16 v[12:15], v[198:201], v[230:233], v[12:15]
	v_mfma_f32_16x16x32_bf16 v[8:11], v[198:201], v[234:237], v[8:11]
	v_mfma_f32_16x16x32_bf16 v[4:7], v[198:201], v[238:241], v[4:7]
	v_mfma_f32_16x16x32_bf16 v[0:3], v[198:201], v[242:245], v[0:3]
	global_load_dwordx4 v[198:201], v[148:149], off offset:384
	ds_read_b128 v[230:233], v16 offset:320
	ds_read_b128 v[234:237], v16 offset:8768
	ds_read_b128 v[238:241], v16 offset:17216
	ds_read_b128 v[242:245], v16 offset:25664
	s_waitcnt vmcnt(11) lgkmcnt(4)
	v_mfma_f32_16x16x32_bf16 v[66:69], v[206:209], v[214:217], v[66:69]
	v_mfma_f32_16x16x32_bf16 v[58:61], v[206:209], v[218:221], v[58:61]
	v_mfma_f32_16x16x32_bf16 v[54:57], v[206:209], v[222:225], v[54:57]
	v_mfma_f32_16x16x32_bf16 v[50:53], v[206:209], v[226:229], v[50:53]
	global_load_dwordx4 v[206:209], v[202:203], off offset:448
	s_waitcnt vmcnt(11)
	v_mfma_f32_16x16x32_bf16 v[46:49], v[246:249], v[214:217], v[46:49]
	v_mfma_f32_16x16x32_bf16 v[42:45], v[246:249], v[218:221], v[42:45]
	v_mfma_f32_16x16x32_bf16 v[38:41], v[246:249], v[222:225], v[38:41]
	v_mfma_f32_16x16x32_bf16 v[34:37], v[246:249], v[226:229], v[34:37]
	global_load_dwordx4 v[246:249], v[210:211], off offset:448
	s_waitcnt vmcnt(11)
	v_mfma_f32_16x16x32_bf16 v[30:33], v[134:137], v[214:217], v[30:33]
	v_mfma_f32_16x16x32_bf16 v[26:29], v[134:137], v[218:221], v[26:29]
	v_mfma_f32_16x16x32_bf16 v[22:25], v[134:137], v[222:225], v[22:25]
	v_mfma_f32_16x16x32_bf16 v[18:21], v[134:137], v[226:229], v[18:21]
	global_load_dwordx4 v[134:137], v[250:251], off offset:448
	s_waitcnt vmcnt(11)
	v_mfma_f32_16x16x32_bf16 v[12:15], v[154:157], v[214:217], v[12:15]
	v_mfma_f32_16x16x32_bf16 v[8:11], v[154:157], v[218:221], v[8:11]
	v_mfma_f32_16x16x32_bf16 v[4:7], v[154:157], v[222:225], v[4:7]
	v_mfma_f32_16x16x32_bf16 v[0:3], v[154:157], v[226:229], v[0:3]
	global_load_dwordx4 v[154:157], v[148:149], off offset:448
	ds_read_b128 v[214:217], v16 offset:384
	ds_read_b128 v[218:221], v16 offset:8832
	ds_read_b128 v[222:225], v16 offset:17280
	ds_read_b128 v[226:229], v16 offset:25728
	s_waitcnt vmcnt(11) lgkmcnt(4)
	v_mfma_f32_16x16x32_bf16 v[66:69], v[172:175], v[230:233], v[66:69]
	v_mfma_f32_16x16x32_bf16 v[58:61], v[172:175], v[234:237], v[58:61]
	v_mfma_f32_16x16x32_bf16 v[54:57], v[172:175], v[238:241], v[54:57]
	v_mfma_f32_16x16x32_bf16 v[50:53], v[172:175], v[242:245], v[50:53]
	s_waitcnt vmcnt(10)
	v_mfma_f32_16x16x32_bf16 v[46:49], v[176:179], v[230:233], v[46:49]
	v_mfma_f32_16x16x32_bf16 v[42:45], v[176:179], v[234:237], v[42:45]
	v_mfma_f32_16x16x32_bf16 v[38:41], v[176:179], v[238:241], v[38:41]
	v_mfma_f32_16x16x32_bf16 v[34:37], v[176:179], v[242:245], v[34:37]
	s_waitcnt vmcnt(9)
	v_mfma_f32_16x16x32_bf16 v[30:33], v[180:183], v[230:233], v[30:33]
	v_mfma_f32_16x16x32_bf16 v[26:29], v[180:183], v[234:237], v[26:29]
	v_mfma_f32_16x16x32_bf16 v[22:25], v[180:183], v[238:241], v[22:25]
	v_mfma_f32_16x16x32_bf16 v[18:21], v[180:183], v[242:245], v[18:21]
	s_waitcnt vmcnt(8)
	v_mfma_f32_16x16x32_bf16 v[12:15], v[166:169], v[230:233], v[12:15]
	v_mfma_f32_16x16x32_bf16 v[8:11], v[166:169], v[234:237], v[8:11]
	v_mfma_f32_16x16x32_bf16 v[4:7], v[166:169], v[238:241], v[4:7]
	v_mfma_f32_16x16x32_bf16 v[0:3], v[166:169], v[242:245], v[0:3]
	ds_read_b128 v[230:233], v16 offset:448
	ds_read_b128 v[234:237], v16 offset:8896
	ds_read_b128 v[238:241], v16 offset:17344
	ds_read_b128 v[242:245], v16 offset:25792
	s_waitcnt vmcnt(7) lgkmcnt(4)
	v_mfma_f32_16x16x32_bf16 v[66:69], v[186:189], v[214:217], v[66:69]
	v_mfma_f32_16x16x32_bf16 v[58:61], v[186:189], v[218:221], v[58:61]
	v_mfma_f32_16x16x32_bf16 v[54:57], v[186:189], v[222:225], v[54:57]
	v_mfma_f32_16x16x32_bf16 v[50:53], v[186:189], v[226:229], v[50:53]
	s_waitcnt vmcnt(6)
	v_mfma_f32_16x16x32_bf16 v[46:49], v[190:193], v[214:217], v[46:49]
	v_mfma_f32_16x16x32_bf16 v[42:45], v[190:193], v[218:221], v[42:45]
	v_mfma_f32_16x16x32_bf16 v[38:41], v[190:193], v[222:225], v[38:41]
	v_mfma_f32_16x16x32_bf16 v[34:37], v[190:193], v[226:229], v[34:37]
	s_waitcnt vmcnt(5)
	v_mfma_f32_16x16x32_bf16 v[30:33], v[194:197], v[214:217], v[30:33]
	v_mfma_f32_16x16x32_bf16 v[26:29], v[194:197], v[218:221], v[26:29]
	v_mfma_f32_16x16x32_bf16 v[22:25], v[194:197], v[222:225], v[22:25]
	v_mfma_f32_16x16x32_bf16 v[18:21], v[194:197], v[226:229], v[18:21]
	s_waitcnt vmcnt(4)
	v_mfma_f32_16x16x32_bf16 v[12:15], v[198:201], v[214:217], v[12:15]
	v_mfma_f32_16x16x32_bf16 v[8:11], v[198:201], v[218:221], v[8:11]
	v_mfma_f32_16x16x32_bf16 v[4:7], v[198:201], v[222:225], v[4:7]
	v_mfma_f32_16x16x32_bf16 v[0:3], v[198:201], v[226:229], v[0:3]
	s_waitcnt vmcnt(3) lgkmcnt(0)
	v_mfma_f32_16x16x32_bf16 v[66:69], v[206:209], v[230:233], v[66:69]
	v_mfma_f32_16x16x32_bf16 v[58:61], v[206:209], v[234:237], v[58:61]
	v_mfma_f32_16x16x32_bf16 v[54:57], v[206:209], v[238:241], v[54:57]
	v_mfma_f32_16x16x32_bf16 v[50:53], v[206:209], v[242:245], v[50:53]
	s_waitcnt vmcnt(2)
	v_mfma_f32_16x16x32_bf16 v[46:49], v[246:249], v[230:233], v[46:49]
	v_mfma_f32_16x16x32_bf16 v[42:45], v[246:249], v[234:237], v[42:45]
	v_mfma_f32_16x16x32_bf16 v[38:41], v[246:249], v[238:241], v[38:41]
	v_mfma_f32_16x16x32_bf16 v[34:37], v[246:249], v[242:245], v[34:37]
	s_waitcnt vmcnt(1)
	v_mfma_f32_16x16x32_bf16 v[30:33], v[134:137], v[230:233], v[30:33]
	v_mfma_f32_16x16x32_bf16 v[26:29], v[134:137], v[234:237], v[26:29]
	v_mfma_f32_16x16x32_bf16 v[22:25], v[134:137], v[238:241], v[22:25]
	v_mfma_f32_16x16x32_bf16 v[18:21], v[134:137], v[242:245], v[18:21]
	s_waitcnt vmcnt(0)
	v_mfma_f32_16x16x32_bf16 v[12:15], v[154:157], v[230:233], v[12:15]
	v_mfma_f32_16x16x32_bf16 v[8:11], v[154:157], v[234:237], v[8:11]
	v_mfma_f32_16x16x32_bf16 v[4:7], v[154:157], v[238:241], v[4:7]
	v_mfma_f32_16x16x32_bf16 v[0:3], v[154:157], v[242:245], v[0:3]
	v_add_u32_e32 v16, 0x200, v16
	s_movk_i32 s0, 0x120
	s_movk_i32 s40, 0xe0
	s_mov_b64 s[0:1], 0
